# first seam uses XCD barrier instead of cooperative-groups sync; no grid barrier between layer-0 FFN2-down GEMM and layer-1 weight prep
# speedup vs baseline: 1.0125x; 1.0084x over previous
; #define LAS __attribute__((address_space(3)))
; __device__ __forceinline__ unsigned xb_ld(unsigned* p)              { return __hip_atomic_load(p, __ATOMIC_RELAXED, __HIP_MEMORY_SCOPE_AGENT); }
; __device__ __forceinline__ unsigned xb_add(unsigned* p, unsigned v) { return __hip_atomic_fetch_add(p, v, __ATOMIC_RELAXED, __HIP_MEMORY_SCOPE_AGENT); }
; __device__ __forceinline__ XcdBarrier xcd_barrier_post(unsigned* bar, volatile LAS unsigned* st) {
;     XcdBarrier b; b.bar = bar; b.x = xb_xcc_id(); b.st = st;
;     if (threadIdx.x == 0) (void)xb_add(&bar[XB_XCNT(b.x)], 1u);
;     return b;
; }
; __device__ __forceinline__ void xcd_barrier_complete(unsigned* bar, unsigned x, unsigned& nloc, unsigned& nx) {
;     const unsigned G = gridDim.x * gridDim.y * gridDim.z;
;     unsigned sum, cnt, mine, sp = 0u;
;     for (;;) {
;         sum = 0u; cnt = 0u; mine = 0u;
; #pragma unroll
;         for (unsigned j = 0; j < 16; ++j) { const unsigned c = xb_ld(&bar[XB_XCNT(j)]); sum += c; cnt += (c > 0u) ? 1u : 0u; mine = (j == x) ? c : mine; }
;         if (sum == G) break;
;         __builtin_amdgcn_s_sleep(1);
;         if ((++sp & 255u) == 0u) { if (xb_ld(&bar[XB_TMO])) break; if (sp > XB_SPIN_CAP) { atomicAdd(&bar[XB_TMO], 1u); break; } }
;     }
;     nloc = mine > 0u ? mine : 1u; nx = cnt > 0u ? cnt : 1u;
; }
; __global__ void __launch_bounds__(512, 2) mega_fwd(Args a) {
;     ...
;     const int ph_lo = a.ph_lo, ph_hi = a.ph_hi;
; #pragma unroll 1
;     for (int ph = ph_lo; ph < ph_hi; ++ph) {
;     ArgP ap = (ArgP)__builtin_amdgcn_kernarg_segment_ptr(); asm volatile("" : "+s"(ap));
;     int tid = threadIdx.x; asm volatile("" : "+v"(tid));
;     int bid = blockIdx.x; asm volatile("" : "+s"(bid));
;     int nbk = gridDim.x; asm volatile("" : "+s"(nbk));
;     unsigned char* ws = ap->ws;
;     unsigned char* wb = ws + WS_W;
;     bf16_t* xn = (bf16_t*)(ws + WS_XN);
;     bf16_t* act = (bf16_t*)(ws + WS_BIG);
;     bf16_t *zA = (bf16_t*)(ws + WS_ZA), *zB = (bf16_t*)(ws + WS_ZB), *zC = (bf16_t*)(ws + WS_ZC), *zG = (bf16_t*)(ws + WS_ZG);
;     float* mF = (float*)(ws + WS_MF); bf16_t* mB = (bf16_t*)(ws + WS_MB);
;     bf16_t *ya = (bf16_t*)(ws + WS_YA), *yb = ya + 512, *yc = ya + 1024, *OP = (bf16_t*)(ws + WS_OP);
;     float* LSE = (float*)(ws + WS_LSE);
;     unsigned* RS = (unsigned*)(ws + WS_RS);
;     const float* x = ap->in[0]; float* out = ap->out;
.LBB0_5:
	s_or_b64 exec, exec, s[4:5]
	s_cmp_ge_i32 s74, s75
	s_cbranch_scc1 .LBB0_614
	s_load_dwordx2 s[4:5], s[92:93], 0xd0
	v_lshrrev_b32_e32 v1, 20, v0
	v_lshrrev_b32_e32 v0, 10, v0
	v_or_b32_e32 v0, v0, v1
	s_movk_i32 s8, 0x1400
	s_waitcnt lgkmcnt(0)
	s_mul_i32 s3, s5, s4
	s_load_dword s4, s[92:93], 0xd8
	s_movk_i32 s9, 0xc00
	s_mov_b32 s16, -2.0
	s_mov_b32 s18, 0xc1900000
	s_mov_b32 s20, 0xc1800000
	s_waitcnt lgkmcnt(0)
	s_mul_i32 s3, s3, s4
	s_add_u32 s4, s72, 0x1200
	v_writelane_b32 v254, s3, 6
	s_addc_u32 s5, s73, 0
	v_writelane_b32 v254, s4, 7
	s_mov_b32 s22, 0xc2080000
	s_mov_b32 s24, 0xc2000000
	v_writelane_b32 v254, s5, 8
	s_add_u32 s4, s72, 0x1400
	s_addc_u32 s5, s73, 0
	v_writelane_b32 v254, s4, 9
	s_mov_b32 s26, 0xc2480000
	s_mov_b32 s28, 0xc2400000
	v_writelane_b32 v254, s5, 10
	s_add_u32 s4, s72, 0x1500
	s_addc_u32 s5, s73, 0
	v_writelane_b32 v254, s4, 11
	v_mbcnt_lo_u32_b32 v1, -1, 0
	v_mov_b32_e32 v2, 0
	v_writelane_b32 v254, s5, 12
	s_add_u32 s4, s72, 0x1600
	s_addc_u32 s5, s73, 0
	v_writelane_b32 v254, s4, 13
	v_mov_b32_e32 v175, 0x358637bd
	v_mov_b32_e32 v180, 0x260
	v_writelane_b32 v254, s5, 14
	s_add_u32 s4, s72, 0x1700
	s_addc_u32 s5, s73, 0
	v_writelane_b32 v254, s4, 15
	s_mov_b32 s17, 0xc0400000
	s_mov_b32 s19, 0xc1980000
	v_writelane_b32 v254, s5, 16
	s_add_u32 s4, s72, 0x1800
	s_addc_u32 s5, s73, 0
	v_writelane_b32 v254, s4, 17
	s_mov_b32 s21, 0xc1880000
	s_mov_b32 s23, 0xc20c0000
	v_writelane_b32 v254, s5, 18
	s_add_u32 s4, s72, 0x1900
	s_addc_u32 s5, s73, 0
	v_writelane_b32 v254, s4, 19
	s_mov_b32 s25, 0xc2040000
	s_mov_b32 s27, 0xc24c0000
	v_writelane_b32 v254, s5, 20
	s_add_u32 s4, s72, 0x1a00
	s_addc_u32 s5, s73, 0
	v_writelane_b32 v254, s4, 21
	s_mov_b32 s29, 0xc2440000
	v_mov_b32_e32 v186, 1
	v_writelane_b32 v254, s5, 22
	s_add_u32 s4, s72, 0x1b00
	s_addc_u32 s5, s73, 0
	v_writelane_b32 v254, s4, 23
	v_mov_b64_e32 v[238:239], 0x100
	v_mov_b64_e32 v[176:177], 0xff
	v_writelane_b32 v254, s5, 24
	s_add_u32 s4, s72, 0x1c00
	s_addc_u32 s5, s73, 0
	v_writelane_b32 v254, s4, 25
	v_mbcnt_hi_u32_b32 v178, -1, v1
	v_mov_b32_e32 v179, 0x7f800000
	v_writelane_b32 v254, s5, 26
	s_add_u32 s4, s72, 0x1d00
	s_addc_u32 s5, s73, 0
	v_writelane_b32 v254, s4, 27
	v_mov_b32_e32 v181, 0xf149f2ca
	v_mov_b32_e32 v182, 0xc00
	v_writelane_b32 v254, s5, 28
	s_add_u32 s4, s72, 0x1e00
	s_addc_u32 s5, s73, 0
	v_writelane_b32 v254, s4, 29
	v_mov_b32_e32 v183, 0x3e38aa3b
	s_movk_i32 s97, 0x1600
	v_writelane_b32 v254, s5, 30
	s_add_u32 s4, s72, 0x1f00
	s_addc_u32 s5, s73, 0
	v_writelane_b32 v254, s4, 31
	s_mov_b32 s6, 0x12800000
	s_mov_b32 s33, 0xf800000
	v_writelane_b32 v254, s5, 32
	s_add_u32 s4, s72, 0x2000
	s_addc_u32 s5, s73, 0
	v_writelane_b32 v254, s4, 33
	s_mov_b32 s96, 0xf149f2ca
	s_mov_b32 s37, 0xc30c0000
	v_writelane_b32 v254, s5, 34
	s_add_u32 s4, s72, 0x2100
	s_addc_u32 s5, s73, 0
	v_writelane_b32 v254, s4, 35
	s_mov_b32 s36, 0x42dc0000
	s_movk_i32 s66, 0x2c00
	v_writelane_b32 v254, s5, 36
	s_add_u32 s4, s72, 0x2200
	s_addc_u32 s5, s73, 0
	v_writelane_b32 v254, s4, 37
	s_movk_i32 s67, 0x7fff
	s_mov_b32 s7, s74
	v_writelane_b32 v254, s5, 38
	s_add_u32 s4, s72, 0x2300
	s_addc_u32 s5, s73, 0
	v_writelane_b32 v254, s4, 39
	s_cmp_eq_u32 s10, 15
	s_mov_b32 s31, 0
	v_writelane_b32 v254, s5, 40
	s_cselect_b64 s[4:5], -1, 0
	v_writelane_b32 v254, s4, 41
	s_cmp_eq_u32 s10, 14
	s_mov_b64 s[34:35], 0x80
	v_writelane_b32 v254, s5, 42
	s_cselect_b64 s[4:5], -1, 0
	v_writelane_b32 v254, s4, 43
	s_cmp_eq_u32 s10, 13
	s_nop 0
	v_writelane_b32 v254, s5, 44
	s_cselect_b64 s[4:5], -1, 0
	v_writelane_b32 v254, s4, 45
	s_cmp_eq_u32 s10, 12
	s_nop 0
	v_writelane_b32 v254, s5, 46
	s_cselect_b64 s[4:5], -1, 0
	v_writelane_b32 v254, s4, 47
	s_cmp_eq_u32 s10, 11
	s_nop 0
	v_writelane_b32 v254, s5, 48
	s_cselect_b64 s[4:5], -1, 0
	v_writelane_b32 v254, s4, 49
	s_cmp_eq_u32 s10, 10
	s_nop 0
	v_writelane_b32 v254, s5, 50
	s_cselect_b64 s[4:5], -1, 0
	v_writelane_b32 v254, s4, 51
	s_cmp_eq_u32 s10, 9
	s_nop 0
	v_writelane_b32 v254, s5, 52
	s_cselect_b64 s[4:5], -1, 0
	v_writelane_b32 v254, s4, 53
	s_cmp_eq_u32 s10, 8
	s_nop 0
	v_writelane_b32 v254, s5, 54
	s_cselect_b64 s[4:5], -1, 0
	v_writelane_b32 v254, s4, 55
	s_cmp_eq_u32 s10, 7
	s_nop 0
	v_writelane_b32 v254, s5, 56
	s_cselect_b64 s[4:5], -1, 0
	v_writelane_b32 v254, s4, 57
	s_cmp_eq_u32 s10, 6
	s_nop 0
	v_writelane_b32 v254, s5, 58
	s_cselect_b64 s[4:5], -1, 0
	v_writelane_b32 v254, s4, 59
	s_cmp_eq_u32 s10, 5
	s_nop 0
	v_writelane_b32 v254, s5, 60
	s_cselect_b64 s[4:5], -1, 0
	v_writelane_b32 v254, s4, 61
	s_cmp_eq_u32 s10, 4
	s_nop 0
	v_writelane_b32 v254, s5, 62
	s_cselect_b64 s[4:5], -1, 0
	v_writelane_b32 v254, s4, 63
	s_cmp_eq_u32 s10, 3
	s_nop 0
	v_writelane_b32 v255, s5, 0
	s_cselect_b64 s[4:5], -1, 0
	v_writelane_b32 v255, s4, 1
	s_cmp_eq_u32 s10, 2
	s_nop 0
	v_writelane_b32 v255, s5, 2
	s_cselect_b64 s[4:5], -1, 0
	v_writelane_b32 v255, s4, 3
	s_cmp_eq_u32 s10, 1
	s_nop 0
	v_writelane_b32 v255, s5, 4
	s_cselect_b64 s[4:5], -1, 0
	v_writelane_b32 v255, s4, 5
	s_cmp_eq_u32 s10, 0
	s_nop 0
	v_writelane_b32 v255, s5, 6
	s_cselect_b64 s[4:5], -1, 0
	s_lshl_b32 s3, s10, 8
	s_add_u32 s0, s0, s3
	v_writelane_b32 v255, s4, 7
	s_addc_u32 s1, s1, 0
	s_mov_b64 s[10:11], s[74:75]
	v_writelane_b32 v255, s5, 8
	s_add_u32 s4, s0, 0x1400
	s_addc_u32 s5, s1, 0
	v_writelane_b32 v255, s4, 9
	s_add_u32 s0, s0, 0x2400
	s_addc_u32 s1, s1, 0
	v_writelane_b32 v255, s5, 10
	v_writelane_b32 v255, s0, 11
	s_mov_b32 s3, 0x44800000
	s_movk_i32 s4, 0x1800
	v_writelane_b32 v255, s1, 12
	s_movk_i32 s0, 0x3ff
	v_and_or_b32 v0, v0, s0, v174
	s_add_u32 s0, s72, 0x4400
	s_addc_u32 s1, s73, 0
	v_writelane_b32 v255, s0, 13
	s_mov_b32 s5, 0x127ff000
	s_nop 0
	v_writelane_b32 v255, s1, 14
	s_add_u32 s0, s72, 0x4500
	s_addc_u32 s1, s73, 0
	v_writelane_b32 v255, s0, 15
	s_nop 1
	v_writelane_b32 v255, s1, 16
	s_add_i32 s0, 0, 0x222e0
	v_writelane_b32 v255, s0, 17
	s_add_i32 s0, 0, 0x1a200
	v_writelane_b32 v255, s0, 18
	s_add_i32 s0, 0, 0x11800
	v_writelane_b32 v255, s0, 19
	s_add_i32 s0, 0, 0x22320
	v_writelane_b32 v255, s0, 20
	s_add_i32 s0, 0, 0x22324
	v_writelane_b32 v255, s0, 21
	v_cmp_eq_u32_e64 s[0:1], 0, v0
	s_nop 1
	v_writelane_b32 v255, s0, 22
	s_nop 1
	v_writelane_b32 v255, s1, 23
	v_writelane_b32 v255, s2, 24
	v_writelane_b32 v255, s92, 25
	s_nop 1
	v_writelane_b32 v255, s93, 26
	v_writelane_b32 v255, s8, 27
	s_nop 1
	v_writelane_b32 v255, s9, 28
	v_writelane_b32 v255, s10, 29
	v_writelane_b32 v255, s11, 30
	s_branch .LBB0_11
.LBB0_9:
	s_waitcnt lgkmcnt(0)

; __device__ __forceinline__ void xcd_barrier(const XcdBarrier& b) {
;     asm volatile("s_waitcnt vmcnt(0)" ::: "memory");
;     __syncthreads();
;     if (threadIdx.x == 0) {
;         unsigned* bar = b.bar;
;         __builtin_amdgcn_s_waitcnt(0);
;         unsigned nloc = b.st[0], nx = b.st[1];
;         if (nloc == 0u) { xcd_barrier_complete(bar, b.x, nloc, nx); b.st[0] = nloc; b.st[1] = nx; }
; __global__ void __launch_bounds__(512, 2) mega_fwd(Args a) {
;     ...
;         if (ph + 1 < ph_hi) { if (ph == ph_lo) grid.sync(); else xcd_barrier(xbar); }
.LBB0_549:
	s_add_i32 s0, s7, 1
	s_cmp_ge_i32 s0, s75
	s_cbranch_scc1 .LBB0_10
	s_cmp_eq_u32 s7, 16
	s_cbranch_scc1 .LBB0_10
	s_mov_b64 s[0:1], -1
	s_waitcnt vmcnt(0)
	s_waitcnt lgkmcnt(0)
	s_barrier
	s_mov_b64 s[0:1], exec
	v_readlane_b32 s10, v254, 4
	v_readlane_b32 s11, v254, 5
	s_and_b64 s[10:11], s[0:1], s[10:11]
	s_mov_b64 exec, s[10:11]
	s_cbranch_execz .LBB0_603
	v_readlane_b32 s10, v255, 20
	s_waitcnt vmcnt(0) expcnt(0) lgkmcnt(0)
	s_nop 0
	v_mov_b32_e32 v0, s10
	ds_read_b32 v3, v0
	v_readlane_b32 s10, v255, 21
	s_waitcnt lgkmcnt(0)
	v_cmp_ne_u32_e32 vcc, 0, v3
	v_mov_b32_e32 v0, s10
	ds_read_b32 v0, v0
	s_cbranch_vccnz .LBB0_567
	s_mov_b32 s10, 1
	s_branch .LBB0_555

; __device__ __forceinline__ void xcd_barrier(const XcdBarrier& b) {
;     ...
;     __syncthreads();
; }
.LBB0_603:
	s_or_b64 exec, exec, s[0:1]
	s_mov_b64 s[0:1], 0
	s_waitcnt lgkmcnt(0)
	s_barrier
	s_branch .LBB0_9
